# previous best plus P1 thin GEMMs (a_low and meta projection): all 4 k-blocks of a wave in one trip with 32 loads in flight
# speedup vs baseline: 1.0006x; 1.0006x over previous
.Lthin_p10_g:
	s_add_i32 s100, s7, 4
	s_cmp_gt_i32 s100, s26
	s_cbranch_scc1 .Lthin_p10_t
	s_mov_b32 s98, s0
	s_ashr_i32 s99, s0, 31
	s_lshl_b64 s[98:99], s[98:99], 1
	v_lshl_add_u64 v[186:187], v[8:9], 0, s[98:99]
	v_lshl_add_u64 v[240:241], v[14:15], 0, s[98:99]
	global_load_dwordx4 v[56:59], v[186:187], off
	global_load_dwordx4 v[60:63], v[240:241], off
	global_load_dwordx4 v[64:67], v[186:187], off offset:16
	global_load_dwordx4 v[68:71], v[240:241], off offset:16
	global_load_dwordx4 v[72:75], v[186:187], off offset:32
	global_load_dwordx4 v[76:79], v[240:241], off offset:32
	global_load_dwordx4 v[80:83], v[186:187], off offset:48
	global_load_dwordx4 v[84:87], v[240:241], off offset:48
	global_load_dwordx4 v[88:91], v[186:187], off offset:256
	global_load_dwordx4 v[92:95], v[240:241], off offset:256
	global_load_dwordx4 v[96:99], v[186:187], off offset:272
	global_load_dwordx4 v[100:103], v[240:241], off offset:272
	global_load_dwordx4 v[104:107], v[186:187], off offset:288
	global_load_dwordx4 v[108:111], v[240:241], off offset:288
	global_load_dwordx4 v[112:115], v[186:187], off offset:304
	global_load_dwordx4 v[116:119], v[240:241], off offset:304
	global_load_dwordx4 v[120:123], v[186:187], off offset:512
	global_load_dwordx4 v[124:127], v[240:241], off offset:512
	global_load_dwordx4 v[128:131], v[186:187], off offset:528
	global_load_dwordx4 v[132:135], v[240:241], off offset:528
	global_load_dwordx4 v[136:139], v[186:187], off offset:544
	global_load_dwordx4 v[140:143], v[240:241], off offset:544
	global_load_dwordx4 v[144:147], v[186:187], off offset:560
	global_load_dwordx4 v[148:151], v[240:241], off offset:560
	global_load_dwordx4 v[152:155], v[186:187], off offset:768
	global_load_dwordx4 v[156:159], v[240:241], off offset:768
	global_load_dwordx4 v[160:163], v[186:187], off offset:784
	global_load_dwordx4 v[164:167], v[240:241], off offset:784
	global_load_dwordx4 v[168:171], v[186:187], off offset:800
	global_load_dwordx4 v[172:175], v[240:241], off offset:800
	global_load_dwordx4 v[176:179], v[186:187], off offset:816
	global_load_dwordx4 v[188:191], v[240:241], off offset:816
	s_add_i32 s7, s7, 4
	s_addk_i32 s0, 0x200
	s_waitcnt vmcnt(30)
	v_mfma_f32_16x16x32_bf16 v[2:5], v[56:59], v[60:63], v[2:5]
	s_waitcnt vmcnt(28)
	v_mfma_f32_16x16x32_bf16 v[2:5], v[64:67], v[68:71], v[2:5]
	s_waitcnt vmcnt(26)
	v_mfma_f32_16x16x32_bf16 v[2:5], v[72:75], v[76:79], v[2:5]
	s_waitcnt vmcnt(24)
	v_mfma_f32_16x16x32_bf16 v[2:5], v[80:83], v[84:87], v[2:5]
	s_waitcnt vmcnt(22)
	v_mfma_f32_16x16x32_bf16 v[2:5], v[88:91], v[92:95], v[2:5]
	s_waitcnt vmcnt(20)
	v_mfma_f32_16x16x32_bf16 v[2:5], v[96:99], v[100:103], v[2:5]
	s_waitcnt vmcnt(18)
	v_mfma_f32_16x16x32_bf16 v[2:5], v[104:107], v[108:111], v[2:5]
	s_waitcnt vmcnt(16)
	v_mfma_f32_16x16x32_bf16 v[2:5], v[112:115], v[116:119], v[2:5]
	s_waitcnt vmcnt(14)
	v_mfma_f32_16x16x32_bf16 v[2:5], v[120:123], v[124:127], v[2:5]
	s_waitcnt vmcnt(12)
	v_mfma_f32_16x16x32_bf16 v[2:5], v[128:131], v[132:135], v[2:5]
	s_waitcnt vmcnt(10)
	v_mfma_f32_16x16x32_bf16 v[2:5], v[136:139], v[140:143], v[2:5]
	s_waitcnt vmcnt(8)
	v_mfma_f32_16x16x32_bf16 v[2:5], v[144:147], v[148:151], v[2:5]
	s_waitcnt vmcnt(6)
	v_mfma_f32_16x16x32_bf16 v[2:5], v[152:155], v[156:159], v[2:5]
	s_waitcnt vmcnt(4)
	v_mfma_f32_16x16x32_bf16 v[2:5], v[160:163], v[164:167], v[2:5]
	s_waitcnt vmcnt(2)
	v_mfma_f32_16x16x32_bf16 v[2:5], v[168:171], v[172:175], v[2:5]
	s_waitcnt vmcnt(0)
	v_mfma_f32_16x16x32_bf16 v[2:5], v[176:179], v[188:191], v[2:5]
	s_branch .Lthin_p10_g
.Lthin_p10_t:
	s_cmp_ge_i32 s7, s26
	s_cbranch_scc1 .LBB0_1733

.Lthin_p11_g:
	s_add_i32 s100, s1, 4
	s_cmp_gt_i32 s100, s26
	s_cbranch_scc1 .Lthin_p11_t
	s_mov_b32 s98, s24
	s_ashr_i32 s99, s24, 31
	s_lshl_b64 s[98:99], s[98:99], 1
	v_lshl_add_u64 v[186:187], v[8:9], 0, s[98:99]
	v_lshl_add_u64 v[240:241], v[14:15], 0, s[98:99]
	global_load_dwordx4 v[56:59], v[186:187], off
	global_load_dwordx4 v[60:63], v[240:241], off
	global_load_dwordx4 v[64:67], v[186:187], off offset:16
	global_load_dwordx4 v[68:71], v[240:241], off offset:16
	global_load_dwordx4 v[72:75], v[186:187], off offset:32
	global_load_dwordx4 v[76:79], v[240:241], off offset:32
	global_load_dwordx4 v[80:83], v[186:187], off offset:48
	global_load_dwordx4 v[84:87], v[240:241], off offset:48
	global_load_dwordx4 v[88:91], v[186:187], off offset:256
	global_load_dwordx4 v[92:95], v[240:241], off offset:256
	global_load_dwordx4 v[96:99], v[186:187], off offset:272
	global_load_dwordx4 v[100:103], v[240:241], off offset:272
	global_load_dwordx4 v[104:107], v[186:187], off offset:288
	global_load_dwordx4 v[108:111], v[240:241], off offset:288
	global_load_dwordx4 v[112:115], v[186:187], off offset:304
	global_load_dwordx4 v[116:119], v[240:241], off offset:304
	global_load_dwordx4 v[120:123], v[186:187], off offset:512
	global_load_dwordx4 v[124:127], v[240:241], off offset:512
	global_load_dwordx4 v[128:131], v[186:187], off offset:528
	global_load_dwordx4 v[132:135], v[240:241], off offset:528
	global_load_dwordx4 v[136:139], v[186:187], off offset:544
	global_load_dwordx4 v[140:143], v[240:241], off offset:544
	global_load_dwordx4 v[144:147], v[186:187], off offset:560
	global_load_dwordx4 v[148:151], v[240:241], off offset:560
	global_load_dwordx4 v[152:155], v[186:187], off offset:768
	global_load_dwordx4 v[156:159], v[240:241], off offset:768
	global_load_dwordx4 v[160:163], v[186:187], off offset:784
	global_load_dwordx4 v[164:167], v[240:241], off offset:784
	global_load_dwordx4 v[168:171], v[186:187], off offset:800
	global_load_dwordx4 v[172:175], v[240:241], off offset:800
	global_load_dwordx4 v[176:179], v[186:187], off offset:816
	global_load_dwordx4 v[188:191], v[240:241], off offset:816
	s_add_i32 s1, s1, 4
	s_addk_i32 s24, 0x200
	s_waitcnt vmcnt(30)
	v_mfma_f32_16x16x32_bf16 v[2:5], v[56:59], v[60:63], v[2:5]
	s_waitcnt vmcnt(28)
	v_mfma_f32_16x16x32_bf16 v[2:5], v[64:67], v[68:71], v[2:5]
	s_waitcnt vmcnt(26)
	v_mfma_f32_16x16x32_bf16 v[2:5], v[72:75], v[76:79], v[2:5]
	s_waitcnt vmcnt(24)
	v_mfma_f32_16x16x32_bf16 v[2:5], v[80:83], v[84:87], v[2:5]
	s_waitcnt vmcnt(22)
	v_mfma_f32_16x16x32_bf16 v[2:5], v[88:91], v[92:95], v[2:5]
	s_waitcnt vmcnt(20)
	v_mfma_f32_16x16x32_bf16 v[2:5], v[96:99], v[100:103], v[2:5]
	s_waitcnt vmcnt(18)
	v_mfma_f32_16x16x32_bf16 v[2:5], v[104:107], v[108:111], v[2:5]
	s_waitcnt vmcnt(16)
	v_mfma_f32_16x16x32_bf16 v[2:5], v[112:115], v[116:119], v[2:5]
	s_waitcnt vmcnt(14)
	v_mfma_f32_16x16x32_bf16 v[2:5], v[120:123], v[124:127], v[2:5]
	s_waitcnt vmcnt(12)
	v_mfma_f32_16x16x32_bf16 v[2:5], v[128:131], v[132:135], v[2:5]
	s_waitcnt vmcnt(10)
	v_mfma_f32_16x16x32_bf16 v[2:5], v[136:139], v[140:143], v[2:5]
	s_waitcnt vmcnt(8)
	v_mfma_f32_16x16x32_bf16 v[2:5], v[144:147], v[148:151], v[2:5]
	s_waitcnt vmcnt(6)
	v_mfma_f32_16x16x32_bf16 v[2:5], v[152:155], v[156:159], v[2:5]
	s_waitcnt vmcnt(4)
	v_mfma_f32_16x16x32_bf16 v[2:5], v[160:163], v[164:167], v[2:5]
	s_waitcnt vmcnt(2)
	v_mfma_f32_16x16x32_bf16 v[2:5], v[168:171], v[172:175], v[2:5]
	s_waitcnt vmcnt(0)
	v_mfma_f32_16x16x32_bf16 v[2:5], v[176:179], v[188:191], v[2:5]
	s_branch .Lthin_p11_g
.Lthin_p11_t:
	s_cmp_ge_i32 s1, s26
	s_cbranch_scc1 .LBB0_1738
.LBB0_1737:
	s_ashr_i32 s25, s24, 31
	s_lshl_b64 s[40:41], s[24:25], 1
	v_lshl_add_u64 v[52:53], v[8:9], 0, s[40:41]
	v_lshl_add_u64 v[54:55], v[14:15], 0, s[40:41]
	global_load_dwordx4 v[20:23], v[52:53], off
	global_load_dwordx4 v[24:27], v[52:53], off offset:16
	global_load_dwordx4 v[28:31], v[54:55], off
	global_load_dwordx4 v[32:35], v[52:53], off offset:32
	global_load_dwordx4 v[36:39], v[54:55], off offset:16
	global_load_dwordx4 v[40:43], v[54:55], off offset:32
	global_load_dwordx4 v[44:47], v[52:53], off offset:48
	global_load_dwordx4 v[48:51], v[54:55], off offset:48
	s_add_i32 s1, s1, 2
	s_addk_i32 s24, 0x100
	s_cmp_lt_i32 s1, s26
	s_waitcnt vmcnt(5)
	v_mfma_f32_16x16x32_bf16 v[2:5], v[20:23], v[28:31], v[2:5]
	global_load_dwordx4 v[20:23], v[52:53], off offset:256
	global_load_dwordx4 v[28:31], v[52:53], off offset:272
	s_waitcnt vmcnt(5)
	v_mfma_f32_16x16x32_bf16 v[2:5], v[24:27], v[36:39], v[2:5]
	global_load_dwordx4 v[24:27], v[54:55], off offset:256
	s_waitcnt vmcnt(5)
	v_mfma_f32_16x16x32_bf16 v[2:5], v[32:35], v[40:43], v[2:5]
	global_load_dwordx4 v[32:35], v[54:55], off offset:272
	global_load_dwordx4 v[36:39], v[52:53], off offset:288
	global_load_dwordx4 v[40:43], v[52:53], off offset:304
	s_waitcnt vmcnt(6)
	v_mfma_f32_16x16x32_bf16 v[2:5], v[44:47], v[48:51], v[2:5]
	s_waitcnt vmcnt(3)
	v_mfma_f32_16x16x32_bf16 v[2:5], v[20:23], v[24:27], v[2:5]
	global_load_dwordx4 v[20:23], v[54:55], off offset:288
	global_load_dwordx4 v[24:27], v[54:55], off offset:304
	s_waitcnt vmcnt(4)
	v_mfma_f32_16x16x32_bf16 v[2:5], v[28:31], v[32:35], v[2:5]
	s_waitcnt vmcnt(1)
	v_mfma_f32_16x16x32_bf16 v[2:5], v[36:39], v[20:23], v[2:5]
	s_waitcnt vmcnt(0)
	v_mfma_f32_16x16x32_bf16 v[2:5], v[40:43], v[24:27], v[2:5]
	s_cbranch_scc1 .LBB0_1737

.Lthin_p12_t:
	s_cmp_ge_i32 s1, s26
	s_cbranch_scc1 .LBB0_1743
.LBB0_1742:
	s_ashr_i32 s25, s24, 31
	s_lshl_b64 s[40:41], s[24:25], 1
	v_lshl_add_u64 v[52:53], v[8:9], 0, s[40:41]
	v_lshl_add_u64 v[54:55], v[14:15], 0, s[40:41]
	global_load_dwordx4 v[20:23], v[52:53], off
	global_load_dwordx4 v[24:27], v[52:53], off offset:16
	global_load_dwordx4 v[28:31], v[54:55], off
	global_load_dwordx4 v[32:35], v[52:53], off offset:32
	global_load_dwordx4 v[36:39], v[54:55], off offset:16
	global_load_dwordx4 v[40:43], v[54:55], off offset:32
	global_load_dwordx4 v[44:47], v[52:53], off offset:48
	global_load_dwordx4 v[48:51], v[54:55], off offset:48
	s_add_i32 s1, s1, 2
	s_addk_i32 s24, 0x100
	s_cmp_lt_i32 s1, s26
	s_waitcnt vmcnt(5)
	v_mfma_f32_16x16x32_bf16 v[2:5], v[20:23], v[28:31], v[2:5]
	global_load_dwordx4 v[20:23], v[52:53], off offset:256
	global_load_dwordx4 v[28:31], v[52:53], off offset:272
	s_waitcnt vmcnt(5)
	v_mfma_f32_16x16x32_bf16 v[2:5], v[24:27], v[36:39], v[2:5]
	global_load_dwordx4 v[24:27], v[54:55], off offset:256
	s_waitcnt vmcnt(5)
	v_mfma_f32_16x16x32_bf16 v[2:5], v[32:35], v[40:43], v[2:5]
	global_load_dwordx4 v[32:35], v[54:55], off offset:272
	global_load_dwordx4 v[36:39], v[52:53], off offset:288
	global_load_dwordx4 v[40:43], v[52:53], off offset:304
	s_waitcnt vmcnt(6)
	v_mfma_f32_16x16x32_bf16 v[2:5], v[44:47], v[48:51], v[2:5]
	s_waitcnt vmcnt(3)
	v_mfma_f32_16x16x32_bf16 v[2:5], v[20:23], v[24:27], v[2:5]
	global_load_dwordx4 v[20:23], v[54:55], off offset:288
	global_load_dwordx4 v[24:27], v[54:55], off offset:304
	s_waitcnt vmcnt(4)
	v_mfma_f32_16x16x32_bf16 v[2:5], v[28:31], v[32:35], v[2:5]
	s_waitcnt vmcnt(1)
	v_mfma_f32_16x16x32_bf16 v[2:5], v[36:39], v[20:23], v[2:5]
	s_waitcnt vmcnt(0)
	v_mfma_f32_16x16x32_bf16 v[2:5], v[40:43], v[24:27], v[2:5]
	s_cbranch_scc1 .LBB0_1742

.Lthin_p13_t:
	s_cmp_ge_i32 s1, s26
	s_cbranch_scc1 .LBB0_1748
.LBB0_1747:
	s_ashr_i32 s25, s24, 31
	s_lshl_b64 s[40:41], s[24:25], 1
	v_lshl_add_u64 v[52:53], v[8:9], 0, s[40:41]
	v_lshl_add_u64 v[54:55], v[14:15], 0, s[40:41]
	global_load_dwordx4 v[20:23], v[52:53], off
	global_load_dwordx4 v[24:27], v[52:53], off offset:16
	global_load_dwordx4 v[28:31], v[54:55], off
	global_load_dwordx4 v[32:35], v[52:53], off offset:32
	global_load_dwordx4 v[36:39], v[54:55], off offset:16
	global_load_dwordx4 v[40:43], v[54:55], off offset:32
	global_load_dwordx4 v[44:47], v[52:53], off offset:48
	global_load_dwordx4 v[48:51], v[54:55], off offset:48
	s_add_i32 s1, s1, 2
	s_addk_i32 s24, 0x100
	s_cmp_lt_i32 s1, s26
	s_waitcnt vmcnt(5)
	v_mfma_f32_16x16x32_bf16 v[2:5], v[20:23], v[28:31], v[2:5]
	global_load_dwordx4 v[20:23], v[52:53], off offset:256
	global_load_dwordx4 v[28:31], v[52:53], off offset:272
	s_waitcnt vmcnt(5)
	v_mfma_f32_16x16x32_bf16 v[2:5], v[24:27], v[36:39], v[2:5]
	global_load_dwordx4 v[24:27], v[54:55], off offset:256
	s_waitcnt vmcnt(5)
	v_mfma_f32_16x16x32_bf16 v[2:5], v[32:35], v[40:43], v[2:5]
	global_load_dwordx4 v[32:35], v[54:55], off offset:272
	global_load_dwordx4 v[36:39], v[52:53], off offset:288
	global_load_dwordx4 v[40:43], v[52:53], off offset:304
	s_waitcnt vmcnt(6)
	v_mfma_f32_16x16x32_bf16 v[2:5], v[44:47], v[48:51], v[2:5]
	s_waitcnt vmcnt(3)
	v_mfma_f32_16x16x32_bf16 v[2:5], v[20:23], v[24:27], v[2:5]
	global_load_dwordx4 v[20:23], v[54:55], off offset:288
	global_load_dwordx4 v[24:27], v[54:55], off offset:304
	s_waitcnt vmcnt(4)
	v_mfma_f32_16x16x32_bf16 v[2:5], v[28:31], v[32:35], v[2:5]
	s_waitcnt vmcnt(1)
	v_mfma_f32_16x16x32_bf16 v[2:5], v[36:39], v[20:23], v[2:5]
	s_waitcnt vmcnt(0)
	v_mfma_f32_16x16x32_bf16 v[2:5], v[40:43], v[24:27], v[2:5]
	s_cbranch_scc1 .LBB0_1747

.Lthin_p14_g:
	s_add_i32 s100, s1, 4
	s_cmp_gt_i32 s100, s26
	s_cbranch_scc1 .Lthin_p14_t
	s_mov_b32 s98, s6
	s_ashr_i32 s99, s6, 31
	s_lshl_b64 s[98:99], s[98:99], 1
	v_lshl_add_u64 v[186:187], v[10:11], 0, s[98:99]
	v_lshl_add_u64 v[240:241], v[14:15], 0, s[98:99]
	global_load_dwordx4 v[56:59], v[186:187], off
	global_load_dwordx4 v[60:63], v[240:241], off
	global_load_dwordx4 v[64:67], v[186:187], off offset:16
	global_load_dwordx4 v[68:71], v[240:241], off offset:16
	global_load_dwordx4 v[72:75], v[186:187], off offset:32
	global_load_dwordx4 v[76:79], v[240:241], off offset:32
	global_load_dwordx4 v[80:83], v[186:187], off offset:48
	global_load_dwordx4 v[84:87], v[240:241], off offset:48
	global_load_dwordx4 v[88:91], v[186:187], off offset:256
	global_load_dwordx4 v[92:95], v[240:241], off offset:256
	global_load_dwordx4 v[96:99], v[186:187], off offset:272
	global_load_dwordx4 v[100:103], v[240:241], off offset:272
	global_load_dwordx4 v[104:107], v[186:187], off offset:288
	global_load_dwordx4 v[108:111], v[240:241], off offset:288
	global_load_dwordx4 v[112:115], v[186:187], off offset:304
	global_load_dwordx4 v[116:119], v[240:241], off offset:304
	global_load_dwordx4 v[120:123], v[186:187], off offset:512
	global_load_dwordx4 v[124:127], v[240:241], off offset:512
	global_load_dwordx4 v[128:131], v[186:187], off offset:528
	global_load_dwordx4 v[132:135], v[240:241], off offset:528
	global_load_dwordx4 v[136:139], v[186:187], off offset:544
	global_load_dwordx4 v[140:143], v[240:241], off offset:544
	global_load_dwordx4 v[144:147], v[186:187], off offset:560
	global_load_dwordx4 v[148:151], v[240:241], off offset:560
	global_load_dwordx4 v[152:155], v[186:187], off offset:768
	global_load_dwordx4 v[156:159], v[240:241], off offset:768
	global_load_dwordx4 v[160:163], v[186:187], off offset:784
	global_load_dwordx4 v[164:167], v[240:241], off offset:784
	global_load_dwordx4 v[168:171], v[186:187], off offset:800
	global_load_dwordx4 v[172:175], v[240:241], off offset:800
	global_load_dwordx4 v[176:179], v[186:187], off offset:816
	global_load_dwordx4 v[188:191], v[240:241], off offset:816
	s_add_i32 s1, s1, 4
	s_addk_i32 s6, 0x200
	s_waitcnt vmcnt(30)
	v_mfma_f32_16x16x32_bf16 v[2:5], v[56:59], v[60:63], v[2:5]
	s_waitcnt vmcnt(28)
	v_mfma_f32_16x16x32_bf16 v[2:5], v[64:67], v[68:71], v[2:5]
	s_waitcnt vmcnt(26)
	v_mfma_f32_16x16x32_bf16 v[2:5], v[72:75], v[76:79], v[2:5]
	s_waitcnt vmcnt(24)
	v_mfma_f32_16x16x32_bf16 v[2:5], v[80:83], v[84:87], v[2:5]
	s_waitcnt vmcnt(22)
	v_mfma_f32_16x16x32_bf16 v[2:5], v[88:91], v[92:95], v[2:5]
	s_waitcnt vmcnt(20)
	v_mfma_f32_16x16x32_bf16 v[2:5], v[96:99], v[100:103], v[2:5]
	s_waitcnt vmcnt(18)
	v_mfma_f32_16x16x32_bf16 v[2:5], v[104:107], v[108:111], v[2:5]
	s_waitcnt vmcnt(16)
	v_mfma_f32_16x16x32_bf16 v[2:5], v[112:115], v[116:119], v[2:5]
	s_waitcnt vmcnt(14)
	v_mfma_f32_16x16x32_bf16 v[2:5], v[120:123], v[124:127], v[2:5]
	s_waitcnt vmcnt(12)
	v_mfma_f32_16x16x32_bf16 v[2:5], v[128:131], v[132:135], v[2:5]
	s_waitcnt vmcnt(10)
	v_mfma_f32_16x16x32_bf16 v[2:5], v[136:139], v[140:143], v[2:5]
	s_waitcnt vmcnt(8)
	v_mfma_f32_16x16x32_bf16 v[2:5], v[144:147], v[148:151], v[2:5]
	s_waitcnt vmcnt(6)
	v_mfma_f32_16x16x32_bf16 v[2:5], v[152:155], v[156:159], v[2:5]
	s_waitcnt vmcnt(4)
	v_mfma_f32_16x16x32_bf16 v[2:5], v[160:163], v[164:167], v[2:5]
	s_waitcnt vmcnt(2)
	v_mfma_f32_16x16x32_bf16 v[2:5], v[168:171], v[172:175], v[2:5]
	s_waitcnt vmcnt(0)
	v_mfma_f32_16x16x32_bf16 v[2:5], v[176:179], v[188:191], v[2:5]
	s_branch .Lthin_p14_g
.Lthin_p14_t:
	s_cmp_ge_i32 s1, s26
	s_cbranch_scc1 .LBB0_1762
.LBB0_1761:
	s_ashr_i32 s7, s6, 31
	s_lshl_b64 s[24:25], s[6:7], 1
	v_lshl_add_u64 v[52:53], v[10:11], 0, s[24:25]
	v_lshl_add_u64 v[54:55], v[14:15], 0, s[24:25]
	global_load_dwordx4 v[20:23], v[52:53], off
	global_load_dwordx4 v[24:27], v[52:53], off offset:16
	global_load_dwordx4 v[28:31], v[54:55], off
	global_load_dwordx4 v[32:35], v[52:53], off offset:32
	global_load_dwordx4 v[36:39], v[54:55], off offset:16
	global_load_dwordx4 v[40:43], v[54:55], off offset:32
	global_load_dwordx4 v[44:47], v[52:53], off offset:48
	global_load_dwordx4 v[48:51], v[54:55], off offset:48
	s_add_i32 s1, s1, 2
	s_addk_i32 s6, 0x100
	s_cmp_ge_i32 s1, s26
	s_waitcnt vmcnt(5)
	v_mfma_f32_16x16x32_bf16 v[2:5], v[20:23], v[28:31], v[2:5]
	global_load_dwordx4 v[20:23], v[52:53], off offset:256
	global_load_dwordx4 v[28:31], v[52:53], off offset:272
	s_waitcnt vmcnt(5)
	v_mfma_f32_16x16x32_bf16 v[2:5], v[24:27], v[36:39], v[2:5]
	global_load_dwordx4 v[24:27], v[54:55], off offset:256
	s_waitcnt vmcnt(5)
	v_mfma_f32_16x16x32_bf16 v[2:5], v[32:35], v[40:43], v[2:5]
	global_load_dwordx4 v[32:35], v[54:55], off offset:272
	global_load_dwordx4 v[36:39], v[52:53], off offset:288
	global_load_dwordx4 v[40:43], v[52:53], off offset:304
	s_waitcnt vmcnt(6)
	v_mfma_f32_16x16x32_bf16 v[2:5], v[44:47], v[48:51], v[2:5]
	s_waitcnt vmcnt(3)
	v_mfma_f32_16x16x32_bf16 v[2:5], v[20:23], v[24:27], v[2:5]
	global_load_dwordx4 v[20:23], v[54:55], off offset:288
	global_load_dwordx4 v[24:27], v[54:55], off offset:304
	s_waitcnt vmcnt(4)
	v_mfma_f32_16x16x32_bf16 v[2:5], v[28:31], v[32:35], v[2:5]
	s_waitcnt vmcnt(1)
	v_mfma_f32_16x16x32_bf16 v[2:5], v[36:39], v[20:23], v[2:5]
	s_waitcnt vmcnt(0)
	v_mfma_f32_16x16x32_bf16 v[2:5], v[40:43], v[24:27], v[2:5]
	s_cbranch_scc0 .LBB0_1761

.Lthin_p15_g:
	s_add_i32 s100, s1, 4
	s_cmp_gt_i32 s100, s26
	s_cbranch_scc1 .Lthin_p15_t
	s_mov_b32 s98, s24
	s_ashr_i32 s99, s24, 31
	s_lshl_b64 s[98:99], s[98:99], 1
	v_lshl_add_u64 v[186:187], v[10:11], 0, s[98:99]
	v_lshl_add_u64 v[240:241], v[14:15], 0, s[98:99]
	global_load_dwordx4 v[56:59], v[186:187], off
	global_load_dwordx4 v[60:63], v[240:241], off
	global_load_dwordx4 v[64:67], v[186:187], off offset:16
	global_load_dwordx4 v[68:71], v[240:241], off offset:16
	global_load_dwordx4 v[72:75], v[186:187], off offset:32
	global_load_dwordx4 v[76:79], v[240:241], off offset:32
	global_load_dwordx4 v[80:83], v[186:187], off offset:48
	global_load_dwordx4 v[84:87], v[240:241], off offset:48
	global_load_dwordx4 v[88:91], v[186:187], off offset:256
	global_load_dwordx4 v[92:95], v[240:241], off offset:256
	global_load_dwordx4 v[96:99], v[186:187], off offset:272
	global_load_dwordx4 v[100:103], v[240:241], off offset:272
	global_load_dwordx4 v[104:107], v[186:187], off offset:288
	global_load_dwordx4 v[108:111], v[240:241], off offset:288
	global_load_dwordx4 v[112:115], v[186:187], off offset:304
	global_load_dwordx4 v[116:119], v[240:241], off offset:304
	global_load_dwordx4 v[120:123], v[186:187], off offset:512
	global_load_dwordx4 v[124:127], v[240:241], off offset:512
	global_load_dwordx4 v[128:131], v[186:187], off offset:528
	global_load_dwordx4 v[132:135], v[240:241], off offset:528
	global_load_dwordx4 v[136:139], v[186:187], off offset:544
	global_load_dwordx4 v[140:143], v[240:241], off offset:544
	global_load_dwordx4 v[144:147], v[186:187], off offset:560
	global_load_dwordx4 v[148:151], v[240:241], off offset:560
	global_load_dwordx4 v[152:155], v[186:187], off offset:768
	global_load_dwordx4 v[156:159], v[240:241], off offset:768
	global_load_dwordx4 v[160:163], v[186:187], off offset:784
	global_load_dwordx4 v[164:167], v[240:241], off offset:784
	global_load_dwordx4 v[168:171], v[186:187], off offset:800
	global_load_dwordx4 v[172:175], v[240:241], off offset:800
	global_load_dwordx4 v[176:179], v[186:187], off offset:816
	global_load_dwordx4 v[188:191], v[240:241], off offset:816
	s_add_i32 s1, s1, 4
	s_addk_i32 s24, 0x200
	s_waitcnt vmcnt(30)
	v_mfma_f32_16x16x32_bf16 v[2:5], v[56:59], v[60:63], v[2:5]
	s_waitcnt vmcnt(28)
	v_mfma_f32_16x16x32_bf16 v[2:5], v[64:67], v[68:71], v[2:5]
	s_waitcnt vmcnt(26)
	v_mfma_f32_16x16x32_bf16 v[2:5], v[72:75], v[76:79], v[2:5]
	s_waitcnt vmcnt(24)
	v_mfma_f32_16x16x32_bf16 v[2:5], v[80:83], v[84:87], v[2:5]
	s_waitcnt vmcnt(22)
	v_mfma_f32_16x16x32_bf16 v[2:5], v[88:91], v[92:95], v[2:5]
	s_waitcnt vmcnt(20)
	v_mfma_f32_16x16x32_bf16 v[2:5], v[96:99], v[100:103], v[2:5]
	s_waitcnt vmcnt(18)
	v_mfma_f32_16x16x32_bf16 v[2:5], v[104:107], v[108:111], v[2:5]
	s_waitcnt vmcnt(16)
	v_mfma_f32_16x16x32_bf16 v[2:5], v[112:115], v[116:119], v[2:5]
	s_waitcnt vmcnt(14)
	v_mfma_f32_16x16x32_bf16 v[2:5], v[120:123], v[124:127], v[2:5]
	s_waitcnt vmcnt(12)
	v_mfma_f32_16x16x32_bf16 v[2:5], v[128:131], v[132:135], v[2:5]
	s_waitcnt vmcnt(10)
	v_mfma_f32_16x16x32_bf16 v[2:5], v[136:139], v[140:143], v[2:5]
	s_waitcnt vmcnt(8)
	v_mfma_f32_16x16x32_bf16 v[2:5], v[144:147], v[148:151], v[2:5]
	s_waitcnt vmcnt(6)
	v_mfma_f32_16x16x32_bf16 v[2:5], v[152:155], v[156:159], v[2:5]
	s_waitcnt vmcnt(4)
	v_mfma_f32_16x16x32_bf16 v[2:5], v[160:163], v[164:167], v[2:5]
	s_waitcnt vmcnt(2)
	v_mfma_f32_16x16x32_bf16 v[2:5], v[168:171], v[172:175], v[2:5]
	s_waitcnt vmcnt(0)
	v_mfma_f32_16x16x32_bf16 v[2:5], v[176:179], v[188:191], v[2:5]
	s_branch .Lthin_p15_g
.Lthin_p15_t:
	s_cmp_ge_i32 s1, s26
	s_cbranch_scc1 .LBB0_1767
.LBB0_1766:
	s_ashr_i32 s25, s24, 31
	s_lshl_b64 s[40:41], s[24:25], 1
	v_lshl_add_u64 v[52:53], v[10:11], 0, s[40:41]
	v_lshl_add_u64 v[54:55], v[14:15], 0, s[40:41]
	global_load_dwordx4 v[20:23], v[52:53], off
	global_load_dwordx4 v[24:27], v[52:53], off offset:16
	global_load_dwordx4 v[28:31], v[54:55], off
	global_load_dwordx4 v[32:35], v[52:53], off offset:32
	global_load_dwordx4 v[36:39], v[54:55], off offset:16
	global_load_dwordx4 v[40:43], v[54:55], off offset:32
	global_load_dwordx4 v[44:47], v[52:53], off offset:48
	global_load_dwordx4 v[48:51], v[54:55], off offset:48
	s_add_i32 s1, s1, 2
	s_addk_i32 s24, 0x100
	s_cmp_lt_i32 s1, s26
	s_waitcnt vmcnt(5)
	v_mfma_f32_16x16x32_bf16 v[2:5], v[20:23], v[28:31], v[2:5]
	global_load_dwordx4 v[20:23], v[52:53], off offset:256
	global_load_dwordx4 v[28:31], v[52:53], off offset:272
	s_waitcnt vmcnt(5)
	v_mfma_f32_16x16x32_bf16 v[2:5], v[24:27], v[36:39], v[2:5]
	global_load_dwordx4 v[24:27], v[54:55], off offset:256
	s_waitcnt vmcnt(5)
	v_mfma_f32_16x16x32_bf16 v[2:5], v[32:35], v[40:43], v[2:5]
	global_load_dwordx4 v[32:35], v[54:55], off offset:272
	global_load_dwordx4 v[36:39], v[52:53], off offset:288
	global_load_dwordx4 v[40:43], v[52:53], off offset:304
	s_waitcnt vmcnt(6)
	v_mfma_f32_16x16x32_bf16 v[2:5], v[44:47], v[48:51], v[2:5]
	s_waitcnt vmcnt(3)
	v_mfma_f32_16x16x32_bf16 v[2:5], v[20:23], v[24:27], v[2:5]
	global_load_dwordx4 v[20:23], v[54:55], off offset:288
	global_load_dwordx4 v[24:27], v[54:55], off offset:304
	s_waitcnt vmcnt(4)
	v_mfma_f32_16x16x32_bf16 v[2:5], v[28:31], v[32:35], v[2:5]
	s_waitcnt vmcnt(1)
	v_mfma_f32_16x16x32_bf16 v[2:5], v[36:39], v[20:23], v[2:5]
	s_waitcnt vmcnt(0)
	v_mfma_f32_16x16x32_bf16 v[2:5], v[40:43], v[24:27], v[2:5]
	s_cbranch_scc1 .LBB0_1766

.Lthin_p16_t:
	s_cmp_ge_i32 s1, s26
	s_cbranch_scc1 .LBB0_1772
.LBB0_1771:
	s_ashr_i32 s25, s24, 31
	s_lshl_b64 s[40:41], s[24:25], 1
	v_lshl_add_u64 v[52:53], v[10:11], 0, s[40:41]
	v_lshl_add_u64 v[54:55], v[14:15], 0, s[40:41]
	global_load_dwordx4 v[20:23], v[52:53], off
	global_load_dwordx4 v[24:27], v[52:53], off offset:16
	global_load_dwordx4 v[28:31], v[54:55], off
	global_load_dwordx4 v[32:35], v[52:53], off offset:32
	global_load_dwordx4 v[36:39], v[54:55], off offset:16
	global_load_dwordx4 v[40:43], v[54:55], off offset:32
	global_load_dwordx4 v[44:47], v[52:53], off offset:48
	global_load_dwordx4 v[48:51], v[54:55], off offset:48
	s_add_i32 s1, s1, 2
	s_addk_i32 s24, 0x100
	s_cmp_lt_i32 s1, s26
	s_waitcnt vmcnt(5)
	v_mfma_f32_16x16x32_bf16 v[2:5], v[20:23], v[28:31], v[2:5]
	global_load_dwordx4 v[20:23], v[52:53], off offset:256
	global_load_dwordx4 v[28:31], v[52:53], off offset:272
	s_waitcnt vmcnt(5)
	v_mfma_f32_16x16x32_bf16 v[2:5], v[24:27], v[36:39], v[2:5]
	global_load_dwordx4 v[24:27], v[54:55], off offset:256
	s_waitcnt vmcnt(5)
	v_mfma_f32_16x16x32_bf16 v[2:5], v[32:35], v[40:43], v[2:5]
	global_load_dwordx4 v[32:35], v[54:55], off offset:272
	global_load_dwordx4 v[36:39], v[52:53], off offset:288
	global_load_dwordx4 v[40:43], v[52:53], off offset:304
	s_waitcnt vmcnt(6)
	v_mfma_f32_16x16x32_bf16 v[2:5], v[44:47], v[48:51], v[2:5]
	s_waitcnt vmcnt(3)
	v_mfma_f32_16x16x32_bf16 v[2:5], v[20:23], v[24:27], v[2:5]
	global_load_dwordx4 v[20:23], v[54:55], off offset:288
	global_load_dwordx4 v[24:27], v[54:55], off offset:304
	s_waitcnt vmcnt(4)
	v_mfma_f32_16x16x32_bf16 v[2:5], v[28:31], v[32:35], v[2:5]
	s_waitcnt vmcnt(1)
	v_mfma_f32_16x16x32_bf16 v[2:5], v[36:39], v[20:23], v[2:5]
	s_waitcnt vmcnt(0)
	v_mfma_f32_16x16x32_bf16 v[2:5], v[40:43], v[24:27], v[2:5]
	s_cbranch_scc1 .LBB0_1771

.Lthin_p17_t:
	s_cmp_ge_i32 s1, s26
	s_cbranch_scc1 .LBB0_1777
.LBB0_1776:
	s_ashr_i32 s25, s24, 31
	s_lshl_b64 s[40:41], s[24:25], 1
	v_lshl_add_u64 v[52:53], v[10:11], 0, s[40:41]
	v_lshl_add_u64 v[54:55], v[14:15], 0, s[40:41]
	global_load_dwordx4 v[20:23], v[52:53], off
	global_load_dwordx4 v[24:27], v[52:53], off offset:16
	global_load_dwordx4 v[28:31], v[54:55], off
	global_load_dwordx4 v[32:35], v[52:53], off offset:32
	global_load_dwordx4 v[36:39], v[54:55], off offset:16
	global_load_dwordx4 v[40:43], v[54:55], off offset:32
	global_load_dwordx4 v[44:47], v[52:53], off offset:48
	global_load_dwordx4 v[48:51], v[54:55], off offset:48
	s_add_i32 s1, s1, 2
	s_addk_i32 s24, 0x100
	s_cmp_lt_i32 s1, s26
	s_waitcnt vmcnt(5)
	v_mfma_f32_16x16x32_bf16 v[2:5], v[20:23], v[28:31], v[2:5]
	global_load_dwordx4 v[20:23], v[52:53], off offset:256
	global_load_dwordx4 v[28:31], v[52:53], off offset:272
	s_waitcnt vmcnt(5)
	v_mfma_f32_16x16x32_bf16 v[2:5], v[24:27], v[36:39], v[2:5]
	global_load_dwordx4 v[24:27], v[54:55], off offset:256
	s_waitcnt vmcnt(5)
	v_mfma_f32_16x16x32_bf16 v[2:5], v[32:35], v[40:43], v[2:5]
	global_load_dwordx4 v[32:35], v[54:55], off offset:272
	global_load_dwordx4 v[36:39], v[52:53], off offset:288
	global_load_dwordx4 v[40:43], v[52:53], off offset:304
	s_waitcnt vmcnt(6)
	v_mfma_f32_16x16x32_bf16 v[2:5], v[44:47], v[48:51], v[2:5]
	s_waitcnt vmcnt(3)
	v_mfma_f32_16x16x32_bf16 v[2:5], v[20:23], v[24:27], v[2:5]
	global_load_dwordx4 v[20:23], v[54:55], off offset:288
	global_load_dwordx4 v[24:27], v[54:55], off offset:304
	s_waitcnt vmcnt(4)
	v_mfma_f32_16x16x32_bf16 v[2:5], v[28:31], v[32:35], v[2:5]
	s_waitcnt vmcnt(1)
	v_mfma_f32_16x16x32_bf16 v[2:5], v[36:39], v[20:23], v[2:5]
	s_waitcnt vmcnt(0)
	v_mfma_f32_16x16x32_bf16 v[2:5], v[40:43], v[24:27], v[2:5]
	s_cbranch_scc1 .LBB0_1776
